# gates block: A-fragment LDS reads prefetched 5 deep + xcv reads hoisted, epilogue lgkmcnt waits removed so b16 LDS writes run asynchronously
# speedup vs baseline: 1.0127x; 1.0127x over previous
; #define LAS __attribute__((address_space(3)))
; DI u32x4 pack8f(const float (&f)[8]) { u32x4 r; r[0] = pk2(f[0], f[1]); r[1] = pk2(f[2], f[3]); r[2] = pk2(f[4], f[5]); r[3] = pk2(f[6], f[7]); return r; }
; DI void phase_rglru(const Params& p, unsigned char* shm) {
;     ...
;             for (int j = 0; j < 3; ++j) {
;                 const int q = tid + 512 * j, cc = q % 24;
;                 float a8[8];
;                 { const f32x4 b0 = *(const LAS f32x4*)(cw + 768 + 8 * cc), b1 = *(const LAS f32x4*)(cw + 768 + 8 * cc + 4);
; #pragma unroll
;                   for (int e = 0; e < 4; ++e) { a8[e] = b0[e]; a8[4 + e] = b1[e]; } }
; #pragma unroll
;                 for (int jj = 0; jj < 4; ++jj) {
;                     float xin[8]; { const u32x4 xraw = *(const LAS u32x4*)(lds + XR + jj * TR + loff[j]); unpack8(xraw, xin); }
;                     const f32x4 w0 = *(const LAS f32x4*)(cw + jj * 192 + 8 * cc), w1 = *(const LAS f32x4*)(cw + jj * 192 + 8 * cc + 4);
; #pragma unroll
;                     for (int e = 0; e < 4; ++e) { a8[e] += w0[e] * xin[e]; a8[4 + e] += w1[e] * xin[4 + e]; }
;                 }
;                 *(LAS u32x4*)(lds + XC + loff[j]) = pack8f(a8);
;             }
.LBB0_845:
	s_waitcnt lgkmcnt(0)
	s_barrier
	ds_read_b128 v[120:123], v178
	ds_read_b128 v[124:127], v178 offset:16
	ds_read_b128 v[128:131], v201
	ds_read_b128 v[132:135], v179
	ds_read_b128 v[136:139], v179 offset:16
	ds_read_b128 v[140:143], v201 offset:400
	ds_read_b128 v[144:147], v179 offset:768
	ds_read_b128 v[148:151], v179 offset:784
	ds_read_b128 v[210:213], v201 offset:800
	ds_read_b128 v[214:217], v179 offset:1536
	ds_read_b128 v[218:221], v179 offset:1552
	ds_read_b128 v[222:225], v201 offset:1200
	ds_read_b128 v[226:229], v179 offset:2304
	ds_read_b128 v[230:233], v179 offset:2320
	s_waitcnt lgkmcnt(11)
	v_lshlrev_b32_e32 v170, 16, v128
	v_and_b32_e32 v171, 0xffff0000, v128
	v_lshlrev_b32_e32 v128, 16, v129
	v_and_b32_e32 v129, 0xffff0000, v129
	s_waitcnt lgkmcnt(10)
	v_pk_fma_f32 v[120:121], v[132:133], v[170:171], v[120:121]
	s_waitcnt lgkmcnt(8)
	v_lshlrev_b32_e32 v132, 16, v140
	v_and_b32_e32 v133, 0xffff0000, v140
	v_pk_fma_f32 v[122:123], v[134:135], v[128:129], v[122:123]
	v_lshlrev_b32_e32 v128, 16, v141
	v_and_b32_e32 v129, 0xffff0000, v141
	s_waitcnt lgkmcnt(7)
	v_pk_fma_f32 v[120:121], v[144:145], v[132:133], v[120:121]
	s_waitcnt lgkmcnt(5)
	v_lshlrev_b32_e32 v132, 16, v210
	v_and_b32_e32 v133, 0xffff0000, v210
	v_pk_fma_f32 v[122:123], v[146:147], v[128:129], v[122:123]
	v_lshlrev_b32_e32 v128, 16, v211
	v_and_b32_e32 v129, 0xffff0000, v211
	s_waitcnt lgkmcnt(4)
	v_pk_fma_f32 v[120:121], v[214:215], v[132:133], v[120:121]
	s_waitcnt lgkmcnt(2)
	v_lshlrev_b32_e32 v132, 16, v222
	v_and_b32_e32 v133, 0xffff0000, v222
	v_pk_fma_f32 v[122:123], v[216:217], v[128:129], v[122:123]
	v_lshlrev_b32_e32 v128, 16, v223
	v_and_b32_e32 v129, 0xffff0000, v223
	s_waitcnt lgkmcnt(1)
	v_pk_fma_f32 v[120:121], v[226:227], v[132:133], v[120:121]
	v_lshlrev_b32_e32 v132, 16, v130
	v_and_b32_e32 v133, 0xffff0000, v130
	v_pk_fma_f32 v[122:123], v[228:229], v[128:129], v[122:123]
	v_lshlrev_b32_e32 v128, 16, v131
	v_and_b32_e32 v129, 0xffff0000, v131
	v_pk_fma_f32 v[124:125], v[136:137], v[132:133], v[124:125]
	v_lshlrev_b32_e32 v132, 16, v142
	v_and_b32_e32 v133, 0xffff0000, v142
	v_pk_fma_f32 v[126:127], v[138:139], v[128:129], v[126:127]
	v_lshlrev_b32_e32 v128, 16, v143
	v_and_b32_e32 v129, 0xffff0000, v143
	v_pk_fma_f32 v[124:125], v[148:149], v[132:133], v[124:125]
	v_lshlrev_b32_e32 v132, 16, v212
	v_and_b32_e32 v133, 0xffff0000, v212
	v_pk_fma_f32 v[126:127], v[150:151], v[128:129], v[126:127]
	v_lshlrev_b32_e32 v128, 16, v213
	v_and_b32_e32 v129, 0xffff0000, v213
	v_pk_fma_f32 v[124:125], v[218:219], v[132:133], v[124:125]
	v_lshlrev_b32_e32 v132, 16, v224
	v_and_b32_e32 v133, 0xffff0000, v224
	v_pk_fma_f32 v[126:127], v[220:221], v[128:129], v[126:127]
	v_lshlrev_b32_e32 v128, 16, v225
	v_and_b32_e32 v129, 0xffff0000, v225
	s_waitcnt lgkmcnt(0)
	v_pk_fma_f32 v[124:125], v[230:231], v[132:133], v[124:125]
	v_pk_fma_f32 v[126:127], v[232:233], v[128:129], v[126:127]
	v_cvt_pk_bf16_f32 v120, v120, v121
	v_cvt_pk_bf16_f32 v121, v122, v123
	v_cvt_pk_bf16_f32 v122, v124, v125
	v_cvt_pk_bf16_f32 v123, v126, v127
	ds_write_b128 v201, v[120:123] offset:26880
	ds_read_b128 v[120:123], v180
	ds_read_b128 v[124:127], v180 offset:16
	ds_read_b128 v[128:131], v202
	ds_read_b128 v[132:135], v181
	ds_read_b128 v[136:139], v181 offset:16
	ds_read_b128 v[140:143], v202 offset:400
	ds_read_b128 v[144:147], v181 offset:768
	ds_read_b128 v[148:151], v181 offset:784
	ds_read_b128 v[210:213], v202 offset:800
	ds_read_b128 v[214:217], v181 offset:1536
	ds_read_b128 v[218:221], v181 offset:1552
	ds_read_b128 v[222:225], v202 offset:1200
	ds_read_b128 v[226:229], v181 offset:2304
	ds_read_b128 v[230:233], v181 offset:2320
	s_waitcnt lgkmcnt(11)
	v_lshlrev_b32_e32 v170, 16, v128
	v_and_b32_e32 v171, 0xffff0000, v128
	v_lshlrev_b32_e32 v128, 16, v129
	v_and_b32_e32 v129, 0xffff0000, v129
	s_waitcnt lgkmcnt(10)
	v_pk_fma_f32 v[120:121], v[132:133], v[170:171], v[120:121]
	s_waitcnt lgkmcnt(8)
	v_lshlrev_b32_e32 v132, 16, v140
	v_and_b32_e32 v133, 0xffff0000, v140
	v_pk_fma_f32 v[122:123], v[134:135], v[128:129], v[122:123]
	v_lshlrev_b32_e32 v128, 16, v141
	v_and_b32_e32 v129, 0xffff0000, v141
	s_waitcnt lgkmcnt(7)
	v_pk_fma_f32 v[120:121], v[144:145], v[132:133], v[120:121]
	s_waitcnt lgkmcnt(5)
	v_lshlrev_b32_e32 v132, 16, v210
	v_and_b32_e32 v133, 0xffff0000, v210
	v_pk_fma_f32 v[122:123], v[146:147], v[128:129], v[122:123]
	v_lshlrev_b32_e32 v128, 16, v211
	v_and_b32_e32 v129, 0xffff0000, v211
	s_waitcnt lgkmcnt(4)
	v_pk_fma_f32 v[120:121], v[214:215], v[132:133], v[120:121]
	s_waitcnt lgkmcnt(2)
	v_lshlrev_b32_e32 v132, 16, v222
	v_and_b32_e32 v133, 0xffff0000, v222
	v_pk_fma_f32 v[122:123], v[216:217], v[128:129], v[122:123]
	v_lshlrev_b32_e32 v128, 16, v223
	v_and_b32_e32 v129, 0xffff0000, v223
	s_waitcnt lgkmcnt(1)
	v_pk_fma_f32 v[120:121], v[226:227], v[132:133], v[120:121]
	v_lshlrev_b32_e32 v132, 16, v130
	v_and_b32_e32 v133, 0xffff0000, v130
	v_pk_fma_f32 v[122:123], v[228:229], v[128:129], v[122:123]
	v_lshlrev_b32_e32 v128, 16, v131
	v_and_b32_e32 v129, 0xffff0000, v131
	v_pk_fma_f32 v[124:125], v[136:137], v[132:133], v[124:125]
	v_lshlrev_b32_e32 v132, 16, v142
	v_and_b32_e32 v133, 0xffff0000, v142
	v_pk_fma_f32 v[126:127], v[138:139], v[128:129], v[126:127]
	v_lshlrev_b32_e32 v128, 16, v143
	v_and_b32_e32 v129, 0xffff0000, v143
	v_pk_fma_f32 v[124:125], v[148:149], v[132:133], v[124:125]
	v_lshlrev_b32_e32 v132, 16, v212
	v_and_b32_e32 v133, 0xffff0000, v212
	v_pk_fma_f32 v[126:127], v[150:151], v[128:129], v[126:127]
	v_lshlrev_b32_e32 v128, 16, v213
	v_and_b32_e32 v129, 0xffff0000, v213
	v_pk_fma_f32 v[124:125], v[218:219], v[132:133], v[124:125]
	v_lshlrev_b32_e32 v132, 16, v224
	v_and_b32_e32 v133, 0xffff0000, v224
	v_pk_fma_f32 v[126:127], v[220:221], v[128:129], v[126:127]
	v_lshlrev_b32_e32 v128, 16, v225
	v_and_b32_e32 v129, 0xffff0000, v225
	s_waitcnt lgkmcnt(0)
; #define LAS __attribute__((address_space(3)))
; DI u32x4 pack8f(const float (&f)[8]) { u32x4 r; r[0] = pk2(f[0], f[1]); r[1] = pk2(f[2], f[3]); r[2] = pk2(f[4], f[5]); r[3] = pk2(f[6], f[7]); return r; }
; DI void phase_rglru(const Params& p, unsigned char* shm) {
;     ...
;             for (int j = 0; j < 3; ++j) {
;                 const int q = tid + 512 * j, cc = q % 24;
;                 float a8[8];
;                 { const f32x4 b0 = *(const LAS f32x4*)(cw + 768 + 8 * cc), b1 = *(const LAS f32x4*)(cw + 768 + 8 * cc + 4);
; #pragma unroll
;                   for (int e = 0; e < 4; ++e) { a8[e] = b0[e]; a8[4 + e] = b1[e]; } }
; #pragma unroll
;                 for (int jj = 0; jj < 4; ++jj) {
;                     float xin[8]; { const u32x4 xraw = *(const LAS u32x4*)(lds + XR + jj * TR + loff[j]); unpack8(xraw, xin); }
;                     const f32x4 w0 = *(const LAS f32x4*)(cw + jj * 192 + 8 * cc), w1 = *(const LAS f32x4*)(cw + jj * 192 + 8 * cc + 4);
; #pragma unroll
;                     for (int e = 0; e < 4; ++e) { a8[e] += w0[e] * xin[e]; a8[4 + e] += w1[e] * xin[4 + e]; }
;                 }
;                 *(LAS u32x4*)(lds + XC + loff[j]) = pack8f(a8);
;             }
;     ...
; #pragma unroll
;                     for (int kk = 0; kk < 6; ++kk)
; #pragma unroll
;                         for (int mt = 0; mt < 4; ++mt) {
;                             const bf16x8 af = *(const LAS bf16x8*)(lds + XC + (16 * mt + fr) * TR + (32 * kk + 8 * fq) * 2);
;                             acc[mt][0] = __builtin_amdgcn_mfma_f32_16x16x32_bf16(af, Bf[u][kk], acc[mt][0], 0, 0, 0);
;                             acc[mt][1] = __builtin_amdgcn_mfma_f32_16x16x32_bf16(af, Bf[2 + u][kk], acc[mt][1], 0, 0, 0);
;                         }
	v_pk_fma_f32 v[124:125], v[230:231], v[132:133], v[124:125]
	v_pk_fma_f32 v[126:127], v[232:233], v[128:129], v[126:127]
	v_cvt_pk_bf16_f32 v120, v120, v121
	v_cvt_pk_bf16_f32 v121, v122, v123
	v_cvt_pk_bf16_f32 v122, v124, v125
	v_cvt_pk_bf16_f32 v123, v126, v127
	ds_write_b128 v202, v[120:123] offset:26880
	ds_read_b128 v[120:123], v182
	ds_read_b128 v[124:127], v182 offset:16
	ds_read_b128 v[128:131], v203
	ds_read_b128 v[132:135], v183
	ds_read_b128 v[136:139], v183 offset:16
	ds_read_b128 v[140:143], v203 offset:400
	ds_read_b128 v[144:147], v183 offset:768
	ds_read_b128 v[148:151], v183 offset:784
	ds_read_b128 v[210:213], v203 offset:800
	ds_read_b128 v[214:217], v183 offset:1536
	ds_read_b128 v[218:221], v183 offset:1552
	ds_read_b128 v[222:225], v203 offset:1200
	ds_read_b128 v[226:229], v183 offset:2304
	ds_read_b128 v[230:233], v183 offset:2320
	s_waitcnt lgkmcnt(11)
	v_lshlrev_b32_e32 v170, 16, v128
	v_and_b32_e32 v171, 0xffff0000, v128
	v_lshlrev_b32_e32 v128, 16, v129
	v_and_b32_e32 v129, 0xffff0000, v129
	s_waitcnt lgkmcnt(10)
	v_pk_fma_f32 v[120:121], v[132:133], v[170:171], v[120:121]
	s_waitcnt lgkmcnt(8)
	v_lshlrev_b32_e32 v132, 16, v140
	v_and_b32_e32 v133, 0xffff0000, v140
	v_pk_fma_f32 v[122:123], v[134:135], v[128:129], v[122:123]
	v_lshlrev_b32_e32 v128, 16, v141
	v_and_b32_e32 v129, 0xffff0000, v141
	s_waitcnt lgkmcnt(7)
	v_pk_fma_f32 v[120:121], v[144:145], v[132:133], v[120:121]
	s_waitcnt lgkmcnt(5)
	v_lshlrev_b32_e32 v132, 16, v210
	v_and_b32_e32 v133, 0xffff0000, v210
	v_pk_fma_f32 v[122:123], v[146:147], v[128:129], v[122:123]
	v_lshlrev_b32_e32 v128, 16, v211
	v_and_b32_e32 v129, 0xffff0000, v211
	s_waitcnt lgkmcnt(4)
	v_pk_fma_f32 v[120:121], v[214:215], v[132:133], v[120:121]
	s_waitcnt lgkmcnt(2)
	v_lshlrev_b32_e32 v132, 16, v222
	v_and_b32_e32 v133, 0xffff0000, v222
	v_pk_fma_f32 v[122:123], v[216:217], v[128:129], v[122:123]
	v_lshlrev_b32_e32 v128, 16, v223
	v_and_b32_e32 v129, 0xffff0000, v223
	s_waitcnt lgkmcnt(1)
	v_pk_fma_f32 v[120:121], v[226:227], v[132:133], v[120:121]
	v_lshlrev_b32_e32 v132, 16, v130
	v_and_b32_e32 v133, 0xffff0000, v130
	v_pk_fma_f32 v[122:123], v[228:229], v[128:129], v[122:123]
	v_lshlrev_b32_e32 v128, 16, v131
	v_and_b32_e32 v129, 0xffff0000, v131
	v_pk_fma_f32 v[124:125], v[136:137], v[132:133], v[124:125]
	v_lshlrev_b32_e32 v132, 16, v142
	v_and_b32_e32 v133, 0xffff0000, v142
	v_pk_fma_f32 v[126:127], v[138:139], v[128:129], v[126:127]
	v_lshlrev_b32_e32 v128, 16, v143
	v_and_b32_e32 v129, 0xffff0000, v143
	v_pk_fma_f32 v[124:125], v[148:149], v[132:133], v[124:125]
	v_lshlrev_b32_e32 v132, 16, v212
	v_and_b32_e32 v133, 0xffff0000, v212
	v_pk_fma_f32 v[126:127], v[150:151], v[128:129], v[126:127]
	v_lshlrev_b32_e32 v128, 16, v213
	v_and_b32_e32 v129, 0xffff0000, v213
	v_pk_fma_f32 v[124:125], v[218:219], v[132:133], v[124:125]
	v_lshlrev_b32_e32 v132, 16, v224
	v_and_b32_e32 v133, 0xffff0000, v224
	v_pk_fma_f32 v[126:127], v[220:221], v[128:129], v[126:127]
	v_lshlrev_b32_e32 v128, 16, v225
	v_and_b32_e32 v129, 0xffff0000, v225
	s_waitcnt lgkmcnt(0)
	v_pk_fma_f32 v[124:125], v[230:231], v[132:133], v[124:125]
	v_pk_fma_f32 v[126:127], v[232:233], v[128:129], v[126:127]
	v_cvt_pk_bf16_f32 v120, v120, v121
	v_cvt_pk_bf16_f32 v121, v122, v123
	v_cvt_pk_bf16_f32 v122, v124, v125
	v_cvt_pk_bf16_f32 v123, v126, v127
	ds_write_b128 v203, v[120:123] offset:26880
	s_waitcnt lgkmcnt(0)
	s_barrier
	ds_read_b128 v[120:123], v204 offset:26880
	ds_read_b128 v[124:127], v204 offset:33280
	ds_read_b128 v[128:131], v204 offset:39680
	ds_read_b128 v[132:135], v204 offset:46080
	ds_read_b128 v[226:229], v204 offset:26944
	s_waitcnt lgkmcnt(4)
	v_mfma_f32_16x16x32_bf16 v[148:151], v[120:123], v[0:3], 0
	v_mfma_f32_16x16x32_bf16 v[144:147], v[120:123], v[48:51], 0
	ds_read_b128 v[230:233], v204 offset:33344
	s_waitcnt lgkmcnt(4)
	v_mfma_f32_16x16x32_bf16 v[140:143], v[124:127], v[0:3], 0
	v_mfma_f32_16x16x32_bf16 v[136:139], v[124:127], v[48:51], 0
	ds_read_b128 v[120:123], v204 offset:39744
	s_waitcnt lgkmcnt(4)
	v_mfma_f32_16x16x32_bf16 v[214:217], v[128:131], v[0:3], 0
	v_mfma_f32_16x16x32_bf16 v[210:213], v[128:131], v[48:51], 0
	ds_read_b128 v[124:127], v204 offset:46144
	s_waitcnt lgkmcnt(4)
	v_mfma_f32_16x16x32_bf16 v[218:221], v[132:135], v[0:3], 0
	v_mfma_f32_16x16x32_bf16 v[222:225], v[132:135], v[48:51], 0
	ds_read_b128 v[128:131], v204 offset:27008
	s_waitcnt lgkmcnt(4)
	v_mfma_f32_16x16x32_bf16 v[148:151], v[226:229], v[4:7], v[148:151]
	v_mfma_f32_16x16x32_bf16 v[144:147], v[226:229], v[52:55], v[144:147]
	ds_read_b128 v[132:135], v204 offset:33408
	s_waitcnt lgkmcnt(4)
	v_mfma_f32_16x16x32_bf16 v[140:143], v[230:233], v[4:7], v[140:143]
	v_mfma_f32_16x16x32_bf16 v[136:139], v[230:233], v[52:55], v[136:139]
	ds_read_b128 v[226:229], v204 offset:39808
	s_waitcnt lgkmcnt(4)
	v_mfma_f32_16x16x32_bf16 v[214:217], v[120:123], v[4:7], v[214:217]
	v_mfma_f32_16x16x32_bf16 v[210:213], v[120:123], v[52:55], v[210:213]
	ds_read_b128 v[230:233], v204 offset:46208
	s_waitcnt lgkmcnt(4)
	v_mfma_f32_16x16x32_bf16 v[218:221], v[124:127], v[4:7], v[218:221]
	v_mfma_f32_16x16x32_bf16 v[222:225], v[124:127], v[52:55], v[222:225]
	ds_read_b128 v[120:123], v204 offset:27072
	s_waitcnt lgkmcnt(4)
	v_mfma_f32_16x16x32_bf16 v[148:151], v[128:131], v[8:11], v[148:151]
	v_mfma_f32_16x16x32_bf16 v[144:147], v[128:131], v[56:59], v[144:147]
	ds_read_b128 v[124:127], v204 offset:33472
	s_waitcnt lgkmcnt(4)
	v_mfma_f32_16x16x32_bf16 v[140:143], v[132:135], v[8:11], v[140:143]
	v_mfma_f32_16x16x32_bf16 v[136:139], v[132:135], v[56:59], v[136:139]
	ds_read_b128 v[128:131], v204 offset:39872
	s_waitcnt lgkmcnt(4)
; #define LAS __attribute__((address_space(3)))
; DI unsigned pk2(float a, float b) { f32x2 v = {a, b}; bf2_t r = __builtin_convertvector(v, bf2_t); return __builtin_bit_cast(unsigned, r); }
; DI void phase_rglru(const Params& p, unsigned char* shm) {
;     ...
; #pragma unroll
;                     for (int kk = 0; kk < 6; ++kk)
; #pragma unroll
;                         for (int mt = 0; mt < 4; ++mt) {
;                             const bf16x8 af = *(const LAS bf16x8*)(lds + XC + (16 * mt + fr) * TR + (32 * kk + 8 * fq) * 2);
;                             acc[mt][0] = __builtin_amdgcn_mfma_f32_16x16x32_bf16(af, Bf[u][kk], acc[mt][0], 0, 0, 0);
;                             acc[mt][1] = __builtin_amdgcn_mfma_f32_16x16x32_bf16(af, Bf[2 + u][kk], acc[mt][1], 0, 0, 0);
;                         }
;                     const int ch = chb + 16 * u + fr;
;                     const float ba = gb[ch], bx = gb[192 + ch], sp = gb[384 + ch];
; #pragma unroll
;                     for (int mt = 0; mt < 4; ++mt)
; #pragma unroll
;                         for (int j = 0; j < 4; ++j) {
;                             const int t = 16 * mt + 4 * fq + j;
;                             const float ea = 1.f + __expf(fminf(-(acc[mt][0][j] + ba), 40.f)), ex = 1.f + __expf(fminf(-(acc[mt][1][j] + bx), 40.f));
;                             const float inv = __builtin_amdgcn_rcpf(ea * ex);
;                             const float r = inv * ex, ig = inv * ea;
;                             const float av = __expf(r * sp), om = 1.f - av;
;                             const float xcv = __uint_as_float((unsigned)*(const LAS bf16_t*)(lds + XC + t * TR + ch * 2) << 16);
;                             const float bt = __builtin_amdgcn_sqrtf(fmaxf(om * (1.f + av), 0.f)) * (ig * xcv);
;                             *(LAS bf16_t*)(lds + LAo + t * TR + ch * 2) = (bf16_t)(pk2(om, 0.f) & 0xffffu);
;                             *(LAS bf16_t*)(lds + BTo + t * TR + ch * 2) = (bf16_t)(pk2(bt, 0.f) & 0xffffu);
;                         }
	v_mfma_f32_16x16x32_bf16 v[214:217], v[226:229], v[8:11], v[214:217]
	v_mfma_f32_16x16x32_bf16 v[210:213], v[226:229], v[56:59], v[210:213]
	ds_read_b128 v[132:135], v204 offset:46272
	s_waitcnt lgkmcnt(4)
	v_mfma_f32_16x16x32_bf16 v[218:221], v[230:233], v[8:11], v[218:221]
	v_mfma_f32_16x16x32_bf16 v[222:225], v[230:233], v[56:59], v[222:225]
	ds_read_b128 v[226:229], v204 offset:27136
	s_waitcnt lgkmcnt(4)
	v_mfma_f32_16x16x32_bf16 v[148:151], v[120:123], v[12:15], v[148:151]
	v_mfma_f32_16x16x32_bf16 v[144:147], v[120:123], v[60:63], v[144:147]
	ds_read_b128 v[230:233], v204 offset:33536
	s_waitcnt lgkmcnt(4)
	v_mfma_f32_16x16x32_bf16 v[140:143], v[124:127], v[12:15], v[140:143]
	v_mfma_f32_16x16x32_bf16 v[136:139], v[124:127], v[60:63], v[136:139]
	ds_read_b128 v[120:123], v204 offset:39936
	s_waitcnt lgkmcnt(4)
	v_mfma_f32_16x16x32_bf16 v[214:217], v[128:131], v[12:15], v[214:217]
	v_mfma_f32_16x16x32_bf16 v[210:213], v[128:131], v[60:63], v[210:213]
	ds_read_b128 v[124:127], v204 offset:46336
	s_waitcnt lgkmcnt(4)
	v_mfma_f32_16x16x32_bf16 v[218:221], v[132:135], v[12:15], v[218:221]
	v_mfma_f32_16x16x32_bf16 v[222:225], v[132:135], v[60:63], v[222:225]
	ds_read_b128 v[128:131], v204 offset:27200
	s_waitcnt lgkmcnt(4)
	v_mfma_f32_16x16x32_bf16 v[148:151], v[226:229], v[16:19], v[148:151]
	v_mfma_f32_16x16x32_bf16 v[144:147], v[226:229], v[64:67], v[144:147]
	ds_read_b128 v[132:135], v204 offset:33600
	s_waitcnt lgkmcnt(4)
	v_mfma_f32_16x16x32_bf16 v[140:143], v[230:233], v[16:19], v[140:143]
	v_mfma_f32_16x16x32_bf16 v[136:139], v[230:233], v[64:67], v[136:139]
	s_waitcnt lgkmcnt(3)
	v_mfma_f32_16x16x32_bf16 v[214:217], v[120:123], v[16:19], v[214:217]
	v_mfma_f32_16x16x32_bf16 v[210:213], v[120:123], v[64:67], v[210:213]
	s_waitcnt lgkmcnt(2)
	v_mfma_f32_16x16x32_bf16 v[218:221], v[124:127], v[16:19], v[218:221]
	v_mfma_f32_16x16x32_bf16 v[222:225], v[124:127], v[64:67], v[222:225]
	s_waitcnt lgkmcnt(1)
	v_mfma_f32_16x16x32_bf16 v[148:151], v[128:131], v[20:23], v[148:151]
	v_mfma_f32_16x16x32_bf16 v[144:147], v[128:131], v[68:71], v[144:147]
	s_waitcnt lgkmcnt(0)
	v_mfma_f32_16x16x32_bf16 v[140:143], v[132:135], v[20:23], v[140:143]
	v_mfma_f32_16x16x32_bf16 v[136:139], v[132:135], v[68:71], v[136:139]
	ds_read_b128 v[120:123], v204 offset:40000
	s_nop 1
	ds_read_b128 v[128:131], v204 offset:46400
	ds_read2st64_b32 v[170:171], v184 offset1:3
	ds_read_b32 v205, v184 offset:1536
	ds_read_u16 v226, v194 offset:26880
	ds_read_u16 v227, v194 offset:27280
	ds_read_u16 v228, v194 offset:27680
	ds_read_u16 v229, v194 offset:28080
	ds_read_u16 v230, v194 offset:33280
	ds_read_u16 v231, v194 offset:33680
	ds_read_u16 v232, v194 offset:34080
	ds_read_u16 v233, v194 offset:34480
	ds_read_u16 v234, v194 offset:39680
	ds_read_u16 v235, v194 offset:40080
	ds_read_u16 v236, v194 offset:40480
	ds_read_u16 v237, v194 offset:40880
	ds_read_u16 v238, v194 offset:46080
	ds_read_u16 v239, v194 offset:46480
	ds_read_u16 v240, v194 offset:46880
	ds_read_u16 v241, v194 offset:47280
	s_waitcnt lgkmcnt(15)
	v_mfma_f32_16x16x32_bf16 v[124:127], v[120:123], v[20:23], v[214:217]
	v_add_f32_e32 v148, v148, v170
	v_add_f32_e32 v144, v144, v171
	v_min_f32_e64 v148, -v148, s93
	v_min_f32_e64 v144, -v144, s93
	v_mul_f32_e32 v148, 0x3fb8aa3b, v148
	v_mul_f32_e32 v144, 0x3fb8aa3b, v144
	v_exp_f32_e32 v148, v148
	v_exp_f32_e32 v144, v144
	v_mfma_f32_16x16x32_bf16 v[120:123], v[120:123], v[68:71], v[210:213]
	v_add_f32_e32 v145, v145, v171
	v_add_f32_e32 v148, 1.0, v148
	v_add_f32_e32 v144, 1.0, v144
	v_mul_f32_e32 v210, v148, v144
	v_rcp_f32_e32 v210, v210
	v_min_f32_e64 v145, -v145, s93
	v_mul_f32_e32 v145, 0x3fb8aa3b, v145
	v_mul_f32_e32 v144, v144, v210
	v_mul_f32_e32 v144, v205, v144
	v_mul_f32_e32 v144, 0x3fb8aa3b, v144
	v_exp_f32_e32 v144, v144
	v_mul_f32_e32 v148, v148, v210
	s_waitcnt lgkmcnt(0)
	v_lshlrev_b32_e32 v211, 16, v226
	v_mul_f32_e32 v148, v148, v211
	v_sub_f32_e32 v210, 1.0, v144
	v_add_f32_e32 v144, 1.0, v144
	v_mul_f32_e32 v144, v210, v144
	v_max_f32_e32 v144, 0, v144
	v_sqrt_f32_e32 v144, v144
	v_exp_f32_e32 v145, v145
	v_add_f32_e32 v140, v140, v170
	v_add_f32_e32 v136, v136, v171
	v_mul_f32_e32 v144, v148, v144
	v_cvt_pk_bf16_f32 v144, v144, s0
	ds_write_b16 v196, v144
	v_add_f32_e32 v144, v149, v170
	v_min_f32_e64 v144, -v144, s93
	v_mul_f32_e32 v144, 0x3fb8aa3b, v144
	v_exp_f32_e32 v144, v144
	v_cvt_pk_bf16_f32 v148, v210, s0
	v_add_f32_e32 v145, 1.0, v145
	ds_write_b16 v195, v148
	v_add_f32_e32 v144, 1.0, v144
	v_mul_f32_e32 v148, v144, v145
	v_rcp_f32_e32 v148, v148
	v_min_f32_e64 v140, -v140, s93
	v_min_f32_e64 v136, -v136, s93
	v_mul_f32_e32 v145, v145, v148
	v_mul_f32_e32 v145, v205, v145
	v_mul_f32_e32 v145, 0x3fb8aa3b, v145
	v_exp_f32_e32 v145, v145
	v_mul_f32_e32 v144, v144, v148
	v_lshlrev_b32_e32 v149, 16, v227
	v_mul_f32_e32 v144, v144, v149
	v_sub_f32_e32 v148, 1.0, v145
	v_add_f32_e32 v145, 1.0, v145
	v_mul_f32_e32 v145, v148, v145
	v_max_f32_e32 v145, 0, v145
	v_sqrt_f32_e32 v145, v145
	v_mul_f32_e32 v140, 0x3fb8aa3b, v140
	v_mul_f32_e32 v136, 0x3fb8aa3b, v136
	v_exp_f32_e32 v140, v140
	v_mul_f32_e32 v144, v144, v145
	v_cvt_pk_bf16_f32 v145, v148, s0
	v_cvt_pk_bf16_f32 v144, v144, s0
	ds_write_b16 v195, v145 offset:400
	ds_write_b16 v196, v144 offset:400
	v_add_f32_e32 v144, v150, v170
	v_add_f32_e32 v145, v146, v171
	v_min_f32_e64 v144, -v144, s93
	v_min_f32_e64 v145, -v145, s93
	v_mul_f32_e32 v144, 0x3fb8aa3b, v144
	v_mul_f32_e32 v145, 0x3fb8aa3b, v145
	v_exp_f32_e32 v144, v144
	v_exp_f32_e32 v145, v145
	v_exp_f32_e32 v136, v136
	v_add_f32_e32 v144, 1.0, v144
	v_add_f32_e32 v145, 1.0, v145
	v_mul_f32_e32 v146, v144, v145
; #define LAS __attribute__((address_space(3)))
; DI unsigned pk2(float a, float b) { f32x2 v = {a, b}; bf2_t r = __builtin_convertvector(v, bf2_t); return __builtin_bit_cast(unsigned, r); }
; DI void phase_rglru(const Params& p, unsigned char* shm) {
;     ...
;                     const int ch = chb + 16 * u + fr;
;                     const float ba = gb[ch], bx = gb[192 + ch], sp = gb[384 + ch];
; #pragma unroll
;                     for (int mt = 0; mt < 4; ++mt)
; #pragma unroll
;                         for (int j = 0; j < 4; ++j) {
;                             const int t = 16 * mt + 4 * fq + j;
;                             const float ea = 1.f + __expf(fminf(-(acc[mt][0][j] + ba), 40.f)), ex = 1.f + __expf(fminf(-(acc[mt][1][j] + bx), 40.f));
;                             const float inv = __builtin_amdgcn_rcpf(ea * ex);
;                             const float r = inv * ex, ig = inv * ea;
;                             const float av = __expf(r * sp), om = 1.f - av;
;                             const float xcv = __uint_as_float((unsigned)*(const LAS bf16_t*)(lds + XC + t * TR + ch * 2) << 16);
;                             const float bt = __builtin_amdgcn_sqrtf(fmaxf(om * (1.f + av), 0.f)) * (ig * xcv);
;                             *(LAS bf16_t*)(lds + LAo + t * TR + ch * 2) = (bf16_t)(pk2(om, 0.f) & 0xffffu);
;                             *(LAS bf16_t*)(lds + BTo + t * TR + ch * 2) = (bf16_t)(pk2(bt, 0.f) & 0xffffu);
;                         }
	v_rcp_f32_e32 v146, v146
	v_lshlrev_b32_e32 v148, 16, v228
	v_add_f32_e32 v140, 1.0, v140
	v_add_f32_e32 v136, 1.0, v136
	v_mul_f32_e32 v145, v145, v146
	v_mul_f32_e32 v145, v205, v145
	v_mul_f32_e32 v145, 0x3fb8aa3b, v145
	v_exp_f32_e32 v145, v145
	v_mul_f32_e32 v144, v144, v146
	v_mul_f32_e32 v144, v144, v148
	v_add_f32_e32 v137, v137, v171
	v_sub_f32_e32 v146, 1.0, v145
	v_add_f32_e32 v145, 1.0, v145
	v_mul_f32_e32 v145, v146, v145
	v_max_f32_e32 v145, 0, v145
	v_sqrt_f32_e32 v145, v145
	v_min_f32_e64 v137, -v137, s93
	v_mul_f32_e32 v137, 0x3fb8aa3b, v137
	v_exp_f32_e32 v137, v137
	v_mul_f32_e32 v144, v144, v145
	v_cvt_pk_bf16_f32 v145, v146, s0
	v_cvt_pk_bf16_f32 v144, v144, s0
	ds_write_b16 v195, v145 offset:800
	ds_write_b16 v196, v144 offset:800
	v_add_f32_e32 v144, v151, v170
	v_add_f32_e32 v145, v147, v171
	v_min_f32_e64 v144, -v144, s93
	v_min_f32_e64 v145, -v145, s93
	v_mul_f32_e32 v144, 0x3fb8aa3b, v144
	v_mul_f32_e32 v145, 0x3fb8aa3b, v145
	v_exp_f32_e32 v144, v144
	v_exp_f32_e32 v145, v145
	v_add_f32_e32 v137, 1.0, v137
	v_add_f32_e32 v144, 1.0, v144
	v_add_f32_e32 v145, 1.0, v145
	v_mul_f32_e32 v146, v144, v145
	v_rcp_f32_e32 v146, v146
	v_lshlrev_b32_e32 v147, 16, v229
	v_add_f32_e32 v124, v124, v170
	v_add_f32_e32 v120, v120, v171
	v_mul_f32_e32 v145, v145, v146
	v_mul_f32_e32 v145, v205, v145
	v_mul_f32_e32 v145, 0x3fb8aa3b, v145
	v_exp_f32_e32 v145, v145
	v_mul_f32_e32 v144, v144, v146
	v_mul_f32_e32 v144, v144, v147
	v_min_f32_e64 v124, -v124, s93
	v_sub_f32_e32 v146, 1.0, v145
	v_add_f32_e32 v145, 1.0, v145
	v_mul_f32_e32 v145, v146, v145
	v_max_f32_e32 v145, 0, v145
	v_sqrt_f32_e32 v145, v145
	v_min_f32_e64 v120, -v120, s93
	v_mul_f32_e32 v124, 0x3fb8aa3b, v124
	v_mul_f32_e32 v120, 0x3fb8aa3b, v120
	v_mul_f32_e32 v144, v144, v145
	v_cvt_pk_bf16_f32 v144, v144, s0
	ds_write_b16 v196, v144 offset:1200
	v_mul_f32_e32 v144, v140, v136
	v_rcp_f32_e32 v144, v144
	v_cvt_pk_bf16_f32 v145, v146, s0
	ds_write_b16 v195, v145 offset:1200
	v_exp_f32_e32 v124, v124
	v_mul_f32_e32 v145, v136, v144
	v_mul_f32_e32 v136, v140, v144
	v_mul_f32_e32 v140, v205, v145
	v_mul_f32_e32 v140, 0x3fb8aa3b, v140
	v_exp_f32_e32 v144, v140
	v_exp_f32_e32 v120, v120
	v_add_f32_e32 v124, 1.0, v124
	v_sub_f32_e32 v140, 1.0, v144
	v_add_f32_e32 v144, 1.0, v144
	v_mul_f32_e32 v144, v140, v144
	v_max_f32_e32 v144, 0, v144
	v_sqrt_f32_e32 v144, v144
	v_lshlrev_b32_e32 v145, 16, v230
	v_mul_f32_e32 v136, v136, v145
	v_cvt_pk_bf16_f32 v140, v140, s0
	v_mul_f32_e32 v136, v144, v136
	v_cvt_pk_bf16_f32 v136, v136, s0
	ds_write_b16 v196, v136 offset:6400
	v_add_f32_e32 v136, v141, v170
	v_min_f32_e64 v136, -v136, s93
	v_mul_f32_e32 v136, 0x3fb8aa3b, v136
	v_exp_f32_e32 v136, v136
	ds_write_b16 v195, v140 offset:6400
	v_add_f32_e32 v120, 1.0, v120
	v_add_f32_e32 v136, 1.0, v136
	v_mul_f32_e32 v140, v136, v137
	v_rcp_f32_e32 v140, v140
	v_lshlrev_b32_e32 v141, 16, v231
	v_add_f32_e32 v121, v121, v171
	v_min_f32_e64 v121, -v121, s93
	v_mul_f32_e32 v137, v137, v140
	v_mul_f32_e32 v137, v205, v137
	v_mul_f32_e32 v137, 0x3fb8aa3b, v137
	v_exp_f32_e32 v137, v137
	v_mul_f32_e32 v136, v136, v140
	v_mul_f32_e32 v136, v136, v141
	v_mul_f32_e32 v121, 0x3fb8aa3b, v121
	v_sub_f32_e32 v140, 1.0, v137
	v_add_f32_e32 v137, 1.0, v137
	v_mul_f32_e32 v137, v140, v137
	v_max_f32_e32 v137, 0, v137
	v_sqrt_f32_e32 v137, v137
	v_exp_f32_e32 v121, v121
	v_mfma_f32_16x16x32_bf16 v[132:135], v[128:131], v[20:23], v[218:221]
	v_mul_f32_e32 v136, v137, v136
	v_cvt_pk_bf16_f32 v137, v140, s0
	v_cvt_pk_bf16_f32 v136, v136, s0
	ds_write_b16 v195, v137 offset:6800
	ds_write_b16 v196, v136 offset:6800
	v_add_f32_e32 v136, v142, v170
	v_add_f32_e32 v137, v138, v171
	v_min_f32_e64 v136, -v136, s93
	v_min_f32_e64 v137, -v137, s93
	v_mul_f32_e32 v136, 0x3fb8aa3b, v136
	v_mul_f32_e32 v137, 0x3fb8aa3b, v137
	v_exp_f32_e32 v136, v136
	v_exp_f32_e32 v137, v137
	v_add_f32_e32 v121, 1.0, v121
	v_add_f32_e32 v136, 1.0, v136
	v_add_f32_e32 v137, 1.0, v137
	v_mul_f32_e32 v138, v136, v137
	v_rcp_f32_e32 v138, v138
	v_lshlrev_b32_e32 v140, 16, v232
	v_mfma_f32_16x16x32_bf16 v[128:131], v[128:131], v[68:71], v[222:225]
	v_mul_f32_e32 v137, v137, v138
	v_mul_f32_e32 v137, v205, v137
	v_mul_f32_e32 v137, 0x3fb8aa3b, v137
	v_exp_f32_e32 v137, v137
	v_mul_f32_e32 v136, v136, v138
	v_mul_f32_e32 v136, v136, v140
	v_sub_f32_e32 v138, 1.0, v137
	v_add_f32_e32 v137, 1.0, v137
	v_mul_f32_e32 v137, v138, v137
	v_max_f32_e32 v137, 0, v137
	v_sqrt_f32_e32 v137, v137
	s_nop 0
	v_mul_f32_e32 v136, v137, v136
	v_cvt_pk_bf16_f32 v137, v138, s0
	v_cvt_pk_bf16_f32 v136, v136, s0
	ds_write_b16 v195, v137 offset:7200
	ds_write_b16 v196, v136 offset:7200
	v_add_f32_e32 v136, v143, v170
	v_add_f32_e32 v137, v139, v171
	v_min_f32_e64 v136, -v136, s93
	v_min_f32_e64 v137, -v137, s93
	v_mul_f32_e32 v136, 0x3fb8aa3b, v136
	v_mul_f32_e32 v137, 0x3fb8aa3b, v137
	v_exp_f32_e32 v136, v136
	v_exp_f32_e32 v137, v137
	v_add_f32_e32 v136, 1.0, v136
	v_add_f32_e32 v137, 1.0, v137
	v_mul_f32_e32 v138, v136, v137
	v_rcp_f32_e32 v138, v138
	v_lshlrev_b32_e32 v139, 16, v233
	v_mul_f32_e32 v137, v137, v138
	v_mul_f32_e32 v137, v205, v137
	v_mul_f32_e32 v137, 0x3fb8aa3b, v137
	v_exp_f32_e32 v137, v137
	v_mul_f32_e32 v136, v136, v138
	v_mul_f32_e32 v136, v136, v139
	v_sub_f32_e32 v138, 1.0, v137
	v_add_f32_e32 v137, 1.0, v137
	v_mul_f32_e32 v137, v138, v137
	v_max_f32_e32 v137, 0, v137
	v_sqrt_f32_e32 v137, v137
	s_nop 0
	v_mul_f32_e32 v136, v137, v136
	v_cvt_pk_bf16_f32 v136, v136, s0
	ds_write_b16 v196, v136 offset:7600
	v_mul_f32_e32 v136, v124, v120
	v_rcp_f32_e32 v136, v136
	v_cvt_pk_bf16_f32 v137, v138, s0
	ds_write_b16 v195, v137 offset:7600
; #define LAS __attribute__((address_space(3)))
; DI unsigned pk2(float a, float b) { f32x2 v = {a, b}; bf2_t r = __builtin_convertvector(v, bf2_t); return __builtin_bit_cast(unsigned, r); }
; DI void phase_rglru(const Params& p, unsigned char* shm) {
;     ...
;                     if (u == 1 && w >= 4) break;
;     ...
;                     const int ch = chb + 16 * u + fr;
;                     const float ba = gb[ch], bx = gb[192 + ch], sp = gb[384 + ch];
; #pragma unroll
;                     for (int mt = 0; mt < 4; ++mt)
; #pragma unroll
;                         for (int j = 0; j < 4; ++j) {
;                             const int t = 16 * mt + 4 * fq + j;
;                             const float ea = 1.f + __expf(fminf(-(acc[mt][0][j] + ba), 40.f)), ex = 1.f + __expf(fminf(-(acc[mt][1][j] + bx), 40.f));
;                             const float inv = __builtin_amdgcn_rcpf(ea * ex);
;                             const float r = inv * ex, ig = inv * ea;
;                             const float av = __expf(r * sp), om = 1.f - av;
;                             const float xcv = __uint_as_float((unsigned)*(const LAS bf16_t*)(lds + XC + t * TR + ch * 2) << 16);
;                             const float bt = __builtin_amdgcn_sqrtf(fmaxf(om * (1.f + av), 0.f)) * (ig * xcv);
;                             *(LAS bf16_t*)(lds + LAo + t * TR + ch * 2) = (bf16_t)(pk2(om, 0.f) & 0xffffu);
;                             *(LAS bf16_t*)(lds + BTo + t * TR + ch * 2) = (bf16_t)(pk2(bt, 0.f) & 0xffffu);
;                         }
	v_mul_f32_e32 v120, v120, v136
	v_mul_f32_e32 v120, v205, v120
	v_mul_f32_e32 v120, 0x3fb8aa3b, v120
	v_exp_f32_e32 v120, v120
	v_mul_f32_e32 v124, v124, v136
	v_lshlrev_b32_e32 v137, 16, v234
	v_mul_f32_e32 v124, v124, v137
	v_sub_f32_e32 v136, 1.0, v120
	v_add_f32_e32 v120, 1.0, v120
	v_mul_f32_e32 v120, v136, v120
	v_max_f32_e32 v120, 0, v120
	v_sqrt_f32_e32 v120, v120
	s_nop 0
	v_mul_f32_e32 v120, v120, v124
	v_cvt_pk_bf16_f32 v120, v120, s0
	ds_write_b16 v196, v120 offset:12800
	v_add_f32_e32 v120, v125, v170
	v_min_f32_e64 v120, -v120, s93
	v_mul_f32_e32 v120, 0x3fb8aa3b, v120
	v_exp_f32_e32 v120, v120
	v_cvt_pk_bf16_f32 v124, v136, s0
	ds_write_b16 v195, v124 offset:12800
	v_add_f32_e32 v120, 1.0, v120
	v_mul_f32_e32 v124, v120, v121
	v_rcp_f32_e32 v124, v124
	v_lshlrev_b32_e32 v125, 16, v235
	v_mul_f32_e32 v121, v121, v124
	v_mul_f32_e32 v121, v205, v121
	v_mul_f32_e32 v121, 0x3fb8aa3b, v121
	v_exp_f32_e32 v121, v121
	v_mul_f32_e32 v120, v120, v124
	v_mul_f32_e32 v120, v120, v125
	v_sub_f32_e32 v124, 1.0, v121
	v_add_f32_e32 v121, 1.0, v121
	v_mul_f32_e32 v121, v124, v121
	v_max_f32_e32 v121, 0, v121
	v_sqrt_f32_e32 v121, v121
	s_nop 0
	v_mul_f32_e32 v120, v121, v120
	v_cvt_pk_bf16_f32 v121, v124, s0
	v_cvt_pk_bf16_f32 v120, v120, s0
	ds_write_b16 v195, v121 offset:13200
	ds_write_b16 v196, v120 offset:13200
	v_add_f32_e32 v120, v126, v170
	v_add_f32_e32 v121, v122, v171
	v_min_f32_e64 v120, -v120, s93
	v_min_f32_e64 v121, -v121, s93
	v_mul_f32_e32 v120, 0x3fb8aa3b, v120
	v_mul_f32_e32 v121, 0x3fb8aa3b, v121
	v_exp_f32_e32 v120, v120
	v_exp_f32_e32 v121, v121
	v_add_f32_e32 v120, 1.0, v120
	v_add_f32_e32 v121, 1.0, v121
	v_mul_f32_e32 v122, v120, v121
	v_rcp_f32_e32 v122, v122
	v_lshlrev_b32_e32 v124, 16, v236
	v_mul_f32_e32 v121, v121, v122
	v_mul_f32_e32 v121, v205, v121
	v_mul_f32_e32 v121, 0x3fb8aa3b, v121
	v_exp_f32_e32 v121, v121
	v_mul_f32_e32 v120, v120, v122
	v_mul_f32_e32 v120, v120, v124
	v_sub_f32_e32 v122, 1.0, v121
	v_add_f32_e32 v121, 1.0, v121
	v_mul_f32_e32 v121, v122, v121
	v_max_f32_e32 v121, 0, v121
	v_sqrt_f32_e32 v121, v121
	s_nop 0
	v_mul_f32_e32 v120, v121, v120
	v_cvt_pk_bf16_f32 v121, v122, s0
	v_cvt_pk_bf16_f32 v120, v120, s0
	ds_write_b16 v195, v121 offset:13600
	ds_write_b16 v196, v120 offset:13600
	v_add_f32_e32 v120, v127, v170
	v_add_f32_e32 v121, v123, v171
	v_min_f32_e64 v120, -v120, s93
	v_min_f32_e64 v121, -v121, s93
	v_mul_f32_e32 v120, 0x3fb8aa3b, v120
	v_mul_f32_e32 v121, 0x3fb8aa3b, v121
	v_exp_f32_e32 v120, v120
	v_exp_f32_e32 v121, v121
	v_add_f32_e32 v120, 1.0, v120
	v_add_f32_e32 v121, 1.0, v121
	v_mul_f32_e32 v122, v120, v121
	v_rcp_f32_e32 v122, v122
	v_lshlrev_b32_e32 v123, 16, v237
	v_mul_f32_e32 v121, v121, v122
	v_mul_f32_e32 v121, v205, v121
	v_mul_f32_e32 v121, 0x3fb8aa3b, v121
	v_exp_f32_e32 v121, v121
	v_mul_f32_e32 v120, v120, v122
	v_mul_f32_e32 v120, v120, v123
	v_sub_f32_e32 v122, 1.0, v121
	v_add_f32_e32 v121, 1.0, v121
	v_mul_f32_e32 v121, v122, v121
	v_max_f32_e32 v121, 0, v121
	v_sqrt_f32_e32 v121, v121
	v_lshlrev_b32_e32 v123, 16, v238
	v_mul_f32_e32 v120, v121, v120
	v_cvt_pk_bf16_f32 v121, v122, s0
	v_cvt_pk_bf16_f32 v120, v120, s0
	ds_write_b16 v195, v121 offset:14000
	ds_write_b16 v196, v120 offset:14000
	v_add_f32_e32 v120, v132, v170
	v_add_f32_e32 v121, v128, v171
	v_min_f32_e64 v120, -v120, s93
	v_min_f32_e64 v121, -v121, s93
	v_mul_f32_e32 v120, 0x3fb8aa3b, v120
	v_mul_f32_e32 v121, 0x3fb8aa3b, v121
	v_exp_f32_e32 v120, v120
	v_exp_f32_e32 v121, v121
	v_add_f32_e32 v120, 1.0, v120
	v_add_f32_e32 v121, 1.0, v121
	v_mul_f32_e32 v122, v120, v121
	v_rcp_f32_e32 v122, v122
	s_nop 0
	v_mul_f32_e32 v121, v121, v122
	v_mul_f32_e32 v121, v205, v121
	v_mul_f32_e32 v121, 0x3fb8aa3b, v121
	v_exp_f32_e32 v121, v121
	v_mul_f32_e32 v120, v120, v122
	v_mul_f32_e32 v120, v120, v123
	v_sub_f32_e32 v122, 1.0, v121
	v_add_f32_e32 v121, 1.0, v121
	v_mul_f32_e32 v121, v122, v121
	v_max_f32_e32 v121, 0, v121
	v_sqrt_f32_e32 v121, v121
	v_lshlrev_b32_e32 v123, 16, v239
	v_mul_f32_e32 v120, v121, v120
	v_cvt_pk_bf16_f32 v121, v122, s0
	v_cvt_pk_bf16_f32 v120, v120, s0
	ds_write_b16 v195, v121 offset:19200
	ds_write_b16 v196, v120 offset:19200
	v_add_f32_e32 v120, v133, v170
	v_add_f32_e32 v121, v129, v171
	v_min_f32_e64 v120, -v120, s93
	v_min_f32_e64 v121, -v121, s93
	v_mul_f32_e32 v120, 0x3fb8aa3b, v120
	v_mul_f32_e32 v121, 0x3fb8aa3b, v121
	v_exp_f32_e32 v120, v120
	v_exp_f32_e32 v121, v121
	v_add_f32_e32 v120, 1.0, v120
	v_add_f32_e32 v121, 1.0, v121
	v_mul_f32_e32 v122, v120, v121
	v_rcp_f32_e32 v122, v122
	s_nop 0
	v_mul_f32_e32 v121, v121, v122
	v_mul_f32_e32 v121, v205, v121
	v_mul_f32_e32 v121, 0x3fb8aa3b, v121
	v_exp_f32_e32 v121, v121
	v_mul_f32_e32 v120, v120, v122
	v_mul_f32_e32 v120, v120, v123
	v_sub_f32_e32 v122, 1.0, v121
	v_add_f32_e32 v121, 1.0, v121
	v_mul_f32_e32 v121, v122, v121
	v_max_f32_e32 v121, 0, v121
	v_sqrt_f32_e32 v121, v121
	v_lshlrev_b32_e32 v123, 16, v240
	v_mul_f32_e32 v120, v121, v120
	v_cvt_pk_bf16_f32 v121, v122, s0
	v_cvt_pk_bf16_f32 v120, v120, s0
	ds_write_b16 v195, v121 offset:19600
	ds_write_b16 v196, v120 offset:19600
	v_add_f32_e32 v120, v134, v170
	v_add_f32_e32 v121, v130, v171
	v_min_f32_e64 v120, -v120, s93
	v_min_f32_e64 v121, -v121, s93
	v_mul_f32_e32 v120, 0x3fb8aa3b, v120
	v_mul_f32_e32 v121, 0x3fb8aa3b, v121
	v_exp_f32_e32 v120, v120
	v_exp_f32_e32 v121, v121
	v_add_f32_e32 v120, 1.0, v120
	v_add_f32_e32 v121, 1.0, v121
	v_mul_f32_e32 v122, v120, v121
	v_rcp_f32_e32 v122, v122
	s_nop 0
	v_mul_f32_e32 v121, v121, v122
	v_mul_f32_e32 v121, v205, v121
	v_mul_f32_e32 v121, 0x3fb8aa3b, v121
	v_exp_f32_e32 v121, v121
	v_mul_f32_e32 v120, v120, v122
	v_mul_f32_e32 v120, v120, v123
	v_sub_f32_e32 v122, 1.0, v121
	v_add_f32_e32 v121, 1.0, v121
	v_mul_f32_e32 v121, v122, v121
	v_max_f32_e32 v121, 0, v121
	v_sqrt_f32_e32 v121, v121
	v_lshlrev_b32_e32 v123, 16, v241
	v_mul_f32_e32 v120, v121, v120
	v_cvt_pk_bf16_f32 v121, v122, s0
	v_cvt_pk_bf16_f32 v120, v120, s0
	ds_write_b16 v195, v121 offset:20000
	ds_write_b16 v196, v120 offset:20000
	v_add_f32_e32 v120, v135, v170
	v_add_f32_e32 v121, v131, v171
	v_min_f32_e64 v120, -v120, s93
	v_min_f32_e64 v121, -v121, s93
	v_mul_f32_e32 v120, 0x3fb8aa3b, v120
	v_mul_f32_e32 v121, 0x3fb8aa3b, v121
	v_exp_f32_e32 v120, v120
	v_exp_f32_e32 v121, v121
	v_add_f32_e32 v120, 1.0, v120
	v_add_f32_e32 v121, 1.0, v121
	v_mul_f32_e32 v122, v120, v121
	v_rcp_f32_e32 v122, v122
	s_nop 0
	v_mul_f32_e32 v121, v121, v122
	v_mul_f32_e32 v121, v205, v121
	v_mul_f32_e32 v121, 0x3fb8aa3b, v121
	v_mul_f32_e32 v120, v120, v122
	v_exp_f32_e32 v122, v121
	v_mul_f32_e32 v120, v120, v123
	v_sub_f32_e32 v121, 1.0, v122
	v_add_f32_e32 v122, 1.0, v122
	v_mul_f32_e32 v122, v121, v122
	v_max_f32_e32 v122, 0, v122
	v_sqrt_f32_e32 v122, v122
	v_cvt_pk_bf16_f32 v121, v121, s0
	ds_write_b16 v195, v121 offset:20400
	v_mul_f32_e32 v120, v122, v120
	v_cvt_pk_bf16_f32 v120, v120, s0
	ds_write_b16 v196, v120 offset:20400
	s_andn2_b64 vcc, exec, s[12:13]
	s_cbranch_vccnz .LBB0_847
; #define LAS __attribute__((address_space(3)))
; DI void phase_rglru(const Params& p, unsigned char* shm) {
;     ...
;                     if (u == 1 && w >= 4) break;
;                     f32x4 acc[4][2];
; #pragma unroll
;                     for (int mt = 0; mt < 4; ++mt) { acc[mt][0] = (f32x4){0.f, 0.f, 0.f, 0.f}; acc[mt][1] = (f32x4){0.f, 0.f, 0.f, 0.f}; }
; #pragma unroll
;                     for (int kk = 0; kk < 6; ++kk)
; #pragma unroll
;                         for (int mt = 0; mt < 4; ++mt) {
;                             const bf16x8 af = *(const LAS bf16x8*)(lds + XC + (16 * mt + fr) * TR + (32 * kk + 8 * fq) * 2);
;                             acc[mt][0] = __builtin_amdgcn_mfma_f32_16x16x32_bf16(af, Bf[u][kk], acc[mt][0], 0, 0, 0);
;                             acc[mt][1] = __builtin_amdgcn_mfma_f32_16x16x32_bf16(af, Bf[2 + u][kk], acc[mt][1], 0, 0, 0);
;                         }
;                     const int ch = chb + 16 * u + fr;
;                     const float ba = gb[ch], bx = gb[192 + ch], sp = gb[384 + ch];
	ds_read_b128 v[120:123], v204 offset:26880
	ds_read_b128 v[124:127], v204 offset:33280
	ds_read_b128 v[128:131], v204 offset:39680
	ds_read_b128 v[132:135], v204 offset:46080
	ds_read_b128 v[226:229], v204 offset:26944
	s_waitcnt lgkmcnt(4)
	v_mfma_f32_16x16x32_bf16 v[148:151], v[120:123], v[24:27], 0
	v_mfma_f32_16x16x32_bf16 v[144:147], v[120:123], v[72:75], 0
	ds_read_b128 v[230:233], v204 offset:33344
	s_waitcnt lgkmcnt(4)
	v_mfma_f32_16x16x32_bf16 v[140:143], v[124:127], v[24:27], 0
	v_mfma_f32_16x16x32_bf16 v[136:139], v[124:127], v[72:75], 0
	ds_read_b128 v[120:123], v204 offset:39744
	s_waitcnt lgkmcnt(4)
	v_mfma_f32_16x16x32_bf16 v[214:217], v[128:131], v[24:27], 0
	v_mfma_f32_16x16x32_bf16 v[210:213], v[128:131], v[72:75], 0
	ds_read_b128 v[124:127], v204 offset:46144
	s_waitcnt lgkmcnt(4)
	v_mfma_f32_16x16x32_bf16 v[218:221], v[132:135], v[24:27], 0
	v_mfma_f32_16x16x32_bf16 v[222:225], v[132:135], v[72:75], 0
	ds_read_b128 v[128:131], v204 offset:27008
	s_waitcnt lgkmcnt(4)
	v_mfma_f32_16x16x32_bf16 v[148:151], v[226:229], v[28:31], v[148:151]
	v_mfma_f32_16x16x32_bf16 v[144:147], v[226:229], v[76:79], v[144:147]
	ds_read_b128 v[132:135], v204 offset:33408
	s_waitcnt lgkmcnt(4)
	v_mfma_f32_16x16x32_bf16 v[140:143], v[230:233], v[28:31], v[140:143]
	v_mfma_f32_16x16x32_bf16 v[136:139], v[230:233], v[76:79], v[136:139]
	ds_read_b128 v[226:229], v204 offset:39808
	s_waitcnt lgkmcnt(4)
	v_mfma_f32_16x16x32_bf16 v[214:217], v[120:123], v[28:31], v[214:217]
	v_mfma_f32_16x16x32_bf16 v[210:213], v[120:123], v[76:79], v[210:213]
	ds_read_b128 v[230:233], v204 offset:46208
	s_waitcnt lgkmcnt(4)
	v_mfma_f32_16x16x32_bf16 v[218:221], v[124:127], v[28:31], v[218:221]
	v_mfma_f32_16x16x32_bf16 v[222:225], v[124:127], v[76:79], v[222:225]
	ds_read_b128 v[120:123], v204 offset:27072
	s_waitcnt lgkmcnt(4)
	v_mfma_f32_16x16x32_bf16 v[148:151], v[128:131], v[32:35], v[148:151]
	v_mfma_f32_16x16x32_bf16 v[144:147], v[128:131], v[80:83], v[144:147]
	ds_read_b128 v[124:127], v204 offset:33472
	s_waitcnt lgkmcnt(4)
	v_mfma_f32_16x16x32_bf16 v[140:143], v[132:135], v[32:35], v[140:143]
	v_mfma_f32_16x16x32_bf16 v[136:139], v[132:135], v[80:83], v[136:139]
	ds_read_b128 v[128:131], v204 offset:39872
	s_waitcnt lgkmcnt(4)
	v_mfma_f32_16x16x32_bf16 v[214:217], v[226:229], v[32:35], v[214:217]
	v_mfma_f32_16x16x32_bf16 v[210:213], v[226:229], v[80:83], v[210:213]
	ds_read_b128 v[132:135], v204 offset:46272
	s_waitcnt lgkmcnt(4)
	v_mfma_f32_16x16x32_bf16 v[218:221], v[230:233], v[32:35], v[218:221]
	v_mfma_f32_16x16x32_bf16 v[222:225], v[230:233], v[80:83], v[222:225]
	ds_read_b128 v[226:229], v204 offset:27136
	s_waitcnt lgkmcnt(4)
	v_mfma_f32_16x16x32_bf16 v[148:151], v[120:123], v[36:39], v[148:151]
	v_mfma_f32_16x16x32_bf16 v[144:147], v[120:123], v[84:87], v[144:147]
	ds_read_b128 v[230:233], v204 offset:33536
	s_waitcnt lgkmcnt(4)
	v_mfma_f32_16x16x32_bf16 v[140:143], v[124:127], v[36:39], v[140:143]
	v_mfma_f32_16x16x32_bf16 v[136:139], v[124:127], v[84:87], v[136:139]
	ds_read_b128 v[120:123], v204 offset:39936
	s_waitcnt lgkmcnt(4)
	v_mfma_f32_16x16x32_bf16 v[214:217], v[128:131], v[36:39], v[214:217]
	v_mfma_f32_16x16x32_bf16 v[210:213], v[128:131], v[84:87], v[210:213]
	ds_read_b128 v[124:127], v204 offset:46336
	s_waitcnt lgkmcnt(4)
	v_mfma_f32_16x16x32_bf16 v[218:221], v[132:135], v[36:39], v[218:221]
	v_mfma_f32_16x16x32_bf16 v[222:225], v[132:135], v[84:87], v[222:225]
	ds_read_b128 v[128:131], v204 offset:27200
	s_waitcnt lgkmcnt(4)
	v_mfma_f32_16x16x32_bf16 v[148:151], v[226:229], v[40:43], v[148:151]
	v_mfma_f32_16x16x32_bf16 v[144:147], v[226:229], v[88:91], v[144:147]
	ds_read_b128 v[132:135], v204 offset:33600
	s_waitcnt lgkmcnt(4)
	v_mfma_f32_16x16x32_bf16 v[140:143], v[230:233], v[40:43], v[140:143]
	v_mfma_f32_16x16x32_bf16 v[136:139], v[230:233], v[88:91], v[136:139]
	s_waitcnt lgkmcnt(3)
	v_mfma_f32_16x16x32_bf16 v[214:217], v[120:123], v[40:43], v[214:217]
	v_mfma_f32_16x16x32_bf16 v[210:213], v[120:123], v[88:91], v[210:213]
	s_waitcnt lgkmcnt(2)
	v_mfma_f32_16x16x32_bf16 v[218:221], v[124:127], v[40:43], v[218:221]
	v_mfma_f32_16x16x32_bf16 v[222:225], v[124:127], v[88:91], v[222:225]
	s_waitcnt lgkmcnt(1)
	v_mfma_f32_16x16x32_bf16 v[148:151], v[128:131], v[44:47], v[148:151]
	v_mfma_f32_16x16x32_bf16 v[144:147], v[128:131], v[92:95], v[144:147]
	s_waitcnt lgkmcnt(0)
	v_mfma_f32_16x16x32_bf16 v[140:143], v[132:135], v[44:47], v[140:143]
	v_mfma_f32_16x16x32_bf16 v[136:139], v[132:135], v[92:95], v[136:139]
	ds_read_b128 v[120:123], v204 offset:40000
	s_nop 1
	ds_read_b128 v[128:131], v204 offset:46400
	ds_read2st64_b32 v[170:171], v185 offset1:3
	ds_read_b32 v205, v185 offset:1536
	ds_read_u16 v226, v197 offset:26880
	ds_read_u16 v227, v197 offset:27280
	ds_read_u16 v228, v197 offset:27680
	ds_read_u16 v229, v197 offset:28080
	ds_read_u16 v230, v197 offset:33280
	ds_read_u16 v231, v197 offset:33680
	ds_read_u16 v232, v197 offset:34080
	ds_read_u16 v233, v197 offset:34480
	ds_read_u16 v234, v197 offset:39680
	ds_read_u16 v235, v197 offset:40080
	ds_read_u16 v236, v197 offset:40480
	ds_read_u16 v237, v197 offset:40880
	ds_read_u16 v238, v197 offset:46080
	ds_read_u16 v239, v197 offset:46480
	ds_read_u16 v240, v197 offset:46880
	ds_read_u16 v241, v197 offset:47280
	s_waitcnt lgkmcnt(15)
; #define LAS __attribute__((address_space(3)))
; DI unsigned pk2(float a, float b) { f32x2 v = {a, b}; bf2_t r = __builtin_convertvector(v, bf2_t); return __builtin_bit_cast(unsigned, r); }
; DI void phase_rglru(const Params& p, unsigned char* shm) {
;     ...
;                     const int ch = chb + 16 * u + fr;
;                     const float ba = gb[ch], bx = gb[192 + ch], sp = gb[384 + ch];
; #pragma unroll
;                     for (int mt = 0; mt < 4; ++mt)
; #pragma unroll
;                         for (int j = 0; j < 4; ++j) {
;                             const int t = 16 * mt + 4 * fq + j;
;                             const float ea = 1.f + __expf(fminf(-(acc[mt][0][j] + ba), 40.f)), ex = 1.f + __expf(fminf(-(acc[mt][1][j] + bx), 40.f));
;                             const float inv = __builtin_amdgcn_rcpf(ea * ex);
;                             const float r = inv * ex, ig = inv * ea;
;                             const float av = __expf(r * sp), om = 1.f - av;
;                             const float xcv = __uint_as_float((unsigned)*(const LAS bf16_t*)(lds + XC + t * TR + ch * 2) << 16);
;                             const float bt = __builtin_amdgcn_sqrtf(fmaxf(om * (1.f + av), 0.f)) * (ig * xcv);
;                             *(LAS bf16_t*)(lds + LAo + t * TR + ch * 2) = (bf16_t)(pk2(om, 0.f) & 0xffffu);
;                             *(LAS bf16_t*)(lds + BTo + t * TR + ch * 2) = (bf16_t)(pk2(bt, 0.f) & 0xffffu);
;                         }
	v_mfma_f32_16x16x32_bf16 v[124:127], v[120:123], v[44:47], v[214:217]
	v_add_f32_e32 v148, v148, v170
	v_add_f32_e32 v144, v144, v171
	v_min_f32_e64 v148, -v148, s93
	v_min_f32_e64 v144, -v144, s93
	v_mul_f32_e32 v148, 0x3fb8aa3b, v148
	v_mul_f32_e32 v144, 0x3fb8aa3b, v144
	v_exp_f32_e32 v148, v148
	v_exp_f32_e32 v144, v144
	v_mfma_f32_16x16x32_bf16 v[120:123], v[120:123], v[92:95], v[210:213]
	v_add_f32_e32 v145, v145, v171
	v_add_f32_e32 v148, 1.0, v148
	v_add_f32_e32 v144, 1.0, v144
	v_mul_f32_e32 v210, v148, v144
	v_rcp_f32_e32 v210, v210
	v_min_f32_e64 v145, -v145, s93
	v_mul_f32_e32 v145, 0x3fb8aa3b, v145
	v_mul_f32_e32 v144, v144, v210
	v_mul_f32_e32 v144, v205, v144
	v_mul_f32_e32 v144, 0x3fb8aa3b, v144
	v_exp_f32_e32 v144, v144
	v_mul_f32_e32 v148, v148, v210
	s_waitcnt lgkmcnt(0)
	v_lshlrev_b32_e32 v211, 16, v226
	v_mul_f32_e32 v148, v148, v211
	v_sub_f32_e32 v210, 1.0, v144
	v_add_f32_e32 v144, 1.0, v144
	v_mul_f32_e32 v144, v210, v144
	v_max_f32_e32 v144, 0, v144
	v_sqrt_f32_e32 v144, v144
	v_exp_f32_e32 v145, v145
	v_add_f32_e32 v140, v140, v170
	v_add_f32_e32 v136, v136, v171
	v_mul_f32_e32 v144, v148, v144
	v_cvt_pk_bf16_f32 v144, v144, s0
	ds_write_b16 v199, v144
	v_add_f32_e32 v144, v149, v170
	v_min_f32_e64 v144, -v144, s93
	v_mul_f32_e32 v144, 0x3fb8aa3b, v144
	v_exp_f32_e32 v144, v144
	v_cvt_pk_bf16_f32 v148, v210, s0
	v_add_f32_e32 v145, 1.0, v145
	ds_write_b16 v198, v148
	v_add_f32_e32 v144, 1.0, v144
	v_mul_f32_e32 v148, v144, v145
	v_rcp_f32_e32 v148, v148
	v_min_f32_e64 v140, -v140, s93
	v_min_f32_e64 v136, -v136, s93
	v_mul_f32_e32 v145, v145, v148
	v_mul_f32_e32 v145, v205, v145
	v_mul_f32_e32 v145, 0x3fb8aa3b, v145
	v_exp_f32_e32 v145, v145
	v_mul_f32_e32 v144, v144, v148
	v_lshlrev_b32_e32 v149, 16, v227
	v_mul_f32_e32 v144, v144, v149
	v_sub_f32_e32 v148, 1.0, v145
	v_add_f32_e32 v145, 1.0, v145
	v_mul_f32_e32 v145, v148, v145
	v_max_f32_e32 v145, 0, v145
	v_sqrt_f32_e32 v145, v145
	v_mul_f32_e32 v140, 0x3fb8aa3b, v140
	v_mul_f32_e32 v136, 0x3fb8aa3b, v136
	v_exp_f32_e32 v140, v140
	v_mul_f32_e32 v144, v144, v145
	v_cvt_pk_bf16_f32 v145, v148, s0
	v_cvt_pk_bf16_f32 v144, v144, s0
	ds_write_b16 v198, v145 offset:400
	ds_write_b16 v199, v144 offset:400
	v_add_f32_e32 v144, v150, v170
	v_add_f32_e32 v145, v146, v171
	v_min_f32_e64 v144, -v144, s93
	v_min_f32_e64 v145, -v145, s93
	v_mul_f32_e32 v144, 0x3fb8aa3b, v144
	v_mul_f32_e32 v145, 0x3fb8aa3b, v145
	v_exp_f32_e32 v144, v144
	v_exp_f32_e32 v145, v145
	v_exp_f32_e32 v136, v136
	v_add_f32_e32 v144, 1.0, v144
	v_add_f32_e32 v145, 1.0, v145
	v_mul_f32_e32 v146, v144, v145
	v_rcp_f32_e32 v146, v146
	v_lshlrev_b32_e32 v148, 16, v228
	v_add_f32_e32 v140, 1.0, v140
	v_add_f32_e32 v136, 1.0, v136
	v_mul_f32_e32 v145, v145, v146
	v_mul_f32_e32 v145, v205, v145
	v_mul_f32_e32 v145, 0x3fb8aa3b, v145
	v_exp_f32_e32 v145, v145
	v_mul_f32_e32 v144, v144, v146
	v_mul_f32_e32 v144, v144, v148
	v_add_f32_e32 v137, v137, v171
	v_sub_f32_e32 v146, 1.0, v145
	v_add_f32_e32 v145, 1.0, v145
	v_mul_f32_e32 v145, v146, v145
	v_max_f32_e32 v145, 0, v145
	v_sqrt_f32_e32 v145, v145
	v_min_f32_e64 v137, -v137, s93
	v_mul_f32_e32 v137, 0x3fb8aa3b, v137
	v_exp_f32_e32 v137, v137
	v_mul_f32_e32 v144, v144, v145
	v_cvt_pk_bf16_f32 v145, v146, s0
	v_cvt_pk_bf16_f32 v144, v144, s0
	ds_write_b16 v198, v145 offset:800
	ds_write_b16 v199, v144 offset:800
	v_add_f32_e32 v144, v151, v170
	v_add_f32_e32 v145, v147, v171
	v_min_f32_e64 v144, -v144, s93
	v_min_f32_e64 v145, -v145, s93
	v_mul_f32_e32 v144, 0x3fb8aa3b, v144
	v_mul_f32_e32 v145, 0x3fb8aa3b, v145
	v_exp_f32_e32 v144, v144
	v_exp_f32_e32 v145, v145
	v_add_f32_e32 v137, 1.0, v137
	v_add_f32_e32 v144, 1.0, v144
	v_add_f32_e32 v145, 1.0, v145
	v_mul_f32_e32 v146, v144, v145
	v_rcp_f32_e32 v146, v146
	v_lshlrev_b32_e32 v147, 16, v229
	v_add_f32_e32 v124, v124, v170
	v_add_f32_e32 v120, v120, v171
	v_mul_f32_e32 v145, v145, v146
	v_mul_f32_e32 v145, v205, v145
	v_mul_f32_e32 v145, 0x3fb8aa3b, v145
	v_exp_f32_e32 v145, v145
	v_mul_f32_e32 v144, v144, v146
	v_mul_f32_e32 v144, v144, v147
	v_min_f32_e64 v124, -v124, s93
	v_sub_f32_e32 v146, 1.0, v145
	v_add_f32_e32 v145, 1.0, v145
	v_mul_f32_e32 v145, v146, v145
	v_max_f32_e32 v145, 0, v145
	v_sqrt_f32_e32 v145, v145
	v_min_f32_e64 v120, -v120, s93
	v_mul_f32_e32 v124, 0x3fb8aa3b, v124
	v_mul_f32_e32 v120, 0x3fb8aa3b, v120
	v_mul_f32_e32 v144, v144, v145
	v_cvt_pk_bf16_f32 v144, v144, s0
	ds_write_b16 v199, v144 offset:1200
	v_mul_f32_e32 v144, v140, v136
	v_rcp_f32_e32 v144, v144
	v_cvt_pk_bf16_f32 v145, v146, s0
	ds_write_b16 v198, v145 offset:1200
	v_exp_f32_e32 v124, v124
	v_mul_f32_e32 v145, v136, v144
	v_mul_f32_e32 v136, v140, v144
	v_mul_f32_e32 v140, v205, v145
	v_mul_f32_e32 v140, 0x3fb8aa3b, v140
	v_exp_f32_e32 v144, v140
	v_exp_f32_e32 v120, v120
	v_add_f32_e32 v124, 1.0, v124
	v_sub_f32_e32 v140, 1.0, v144
	v_add_f32_e32 v144, 1.0, v144
	v_mul_f32_e32 v144, v140, v144
	v_max_f32_e32 v144, 0, v144
	v_sqrt_f32_e32 v144, v144
	v_lshlrev_b32_e32 v145, 16, v230
	v_mul_f32_e32 v136, v136, v145
	v_cvt_pk_bf16_f32 v140, v140, s0
	v_mul_f32_e32 v136, v144, v136
	v_cvt_pk_bf16_f32 v136, v136, s0
	ds_write_b16 v199, v136 offset:6400
	v_add_f32_e32 v136, v141, v170
	v_min_f32_e64 v136, -v136, s93
	v_mul_f32_e32 v136, 0x3fb8aa3b, v136
	v_exp_f32_e32 v136, v136
	ds_write_b16 v198, v140 offset:6400
	v_add_f32_e32 v120, 1.0, v120
	v_add_f32_e32 v136, 1.0, v136
	v_mul_f32_e32 v140, v136, v137
	v_rcp_f32_e32 v140, v140
	v_lshlrev_b32_e32 v141, 16, v231
	v_add_f32_e32 v121, v121, v171
	v_min_f32_e64 v121, -v121, s93
	v_mul_f32_e32 v137, v137, v140
	v_mul_f32_e32 v137, v205, v137
; #define LAS __attribute__((address_space(3)))
; DI unsigned pk2(float a, float b) { f32x2 v = {a, b}; bf2_t r = __builtin_convertvector(v, bf2_t); return __builtin_bit_cast(unsigned, r); }
; DI void phase_rglru(const Params& p, unsigned char* shm) {
;     ...
;                     const int ch = chb + 16 * u + fr;
;                     const float ba = gb[ch], bx = gb[192 + ch], sp = gb[384 + ch];
; #pragma unroll
;                     for (int mt = 0; mt < 4; ++mt)
; #pragma unroll
;                         for (int j = 0; j < 4; ++j) {
;                             const int t = 16 * mt + 4 * fq + j;
;                             const float ea = 1.f + __expf(fminf(-(acc[mt][0][j] + ba), 40.f)), ex = 1.f + __expf(fminf(-(acc[mt][1][j] + bx), 40.f));
;                             const float inv = __builtin_amdgcn_rcpf(ea * ex);
;                             const float r = inv * ex, ig = inv * ea;
;                             const float av = __expf(r * sp), om = 1.f - av;
;                             const float xcv = __uint_as_float((unsigned)*(const LAS bf16_t*)(lds + XC + t * TR + ch * 2) << 16);
;                             const float bt = __builtin_amdgcn_sqrtf(fmaxf(om * (1.f + av), 0.f)) * (ig * xcv);
;                             *(LAS bf16_t*)(lds + LAo + t * TR + ch * 2) = (bf16_t)(pk2(om, 0.f) & 0xffffu);
;                             *(LAS bf16_t*)(lds + BTo + t * TR + ch * 2) = (bf16_t)(pk2(bt, 0.f) & 0xffffu);
;                         }
	v_mul_f32_e32 v137, 0x3fb8aa3b, v137
	v_exp_f32_e32 v137, v137
	v_mul_f32_e32 v136, v136, v140
	v_mul_f32_e32 v136, v136, v141
	v_mul_f32_e32 v121, 0x3fb8aa3b, v121
	v_sub_f32_e32 v140, 1.0, v137
	v_add_f32_e32 v137, 1.0, v137
	v_mul_f32_e32 v137, v140, v137
	v_max_f32_e32 v137, 0, v137
	v_sqrt_f32_e32 v137, v137
	v_exp_f32_e32 v121, v121
	v_mfma_f32_16x16x32_bf16 v[132:135], v[128:131], v[44:47], v[218:221]
	v_mul_f32_e32 v136, v137, v136
	v_cvt_pk_bf16_f32 v137, v140, s0
	v_cvt_pk_bf16_f32 v136, v136, s0
	ds_write_b16 v198, v137 offset:6800
	ds_write_b16 v199, v136 offset:6800
	v_add_f32_e32 v136, v142, v170
	v_add_f32_e32 v137, v138, v171
	v_min_f32_e64 v136, -v136, s93
	v_min_f32_e64 v137, -v137, s93
	v_mul_f32_e32 v136, 0x3fb8aa3b, v136
	v_mul_f32_e32 v137, 0x3fb8aa3b, v137
	v_exp_f32_e32 v136, v136
	v_exp_f32_e32 v137, v137
	v_add_f32_e32 v121, 1.0, v121
	v_add_f32_e32 v136, 1.0, v136
	v_add_f32_e32 v137, 1.0, v137
	v_mul_f32_e32 v138, v136, v137
	v_rcp_f32_e32 v138, v138
	v_lshlrev_b32_e32 v140, 16, v232
	v_mfma_f32_16x16x32_bf16 v[128:131], v[128:131], v[92:95], v[222:225]
	v_mul_f32_e32 v137, v137, v138
	v_mul_f32_e32 v137, v205, v137
	v_mul_f32_e32 v137, 0x3fb8aa3b, v137
	v_exp_f32_e32 v137, v137
	v_mul_f32_e32 v136, v136, v138
	v_mul_f32_e32 v136, v136, v140
	v_sub_f32_e32 v138, 1.0, v137
	v_add_f32_e32 v137, 1.0, v137
	v_mul_f32_e32 v137, v138, v137
	v_max_f32_e32 v137, 0, v137
	v_sqrt_f32_e32 v137, v137
	s_nop 0
	v_mul_f32_e32 v136, v137, v136
	v_cvt_pk_bf16_f32 v137, v138, s0
	v_cvt_pk_bf16_f32 v136, v136, s0
	ds_write_b16 v198, v137 offset:7200
	ds_write_b16 v199, v136 offset:7200
	v_add_f32_e32 v136, v143, v170
	v_add_f32_e32 v137, v139, v171
	v_min_f32_e64 v136, -v136, s93
	v_min_f32_e64 v137, -v137, s93
	v_mul_f32_e32 v136, 0x3fb8aa3b, v136
	v_mul_f32_e32 v137, 0x3fb8aa3b, v137
	v_exp_f32_e32 v136, v136
	v_exp_f32_e32 v137, v137
	v_add_f32_e32 v136, 1.0, v136
	v_add_f32_e32 v137, 1.0, v137
	v_mul_f32_e32 v138, v136, v137
	v_rcp_f32_e32 v138, v138
	v_lshlrev_b32_e32 v139, 16, v233
	v_mul_f32_e32 v137, v137, v138
	v_mul_f32_e32 v137, v205, v137
	v_mul_f32_e32 v137, 0x3fb8aa3b, v137
	v_exp_f32_e32 v137, v137
	v_mul_f32_e32 v136, v136, v138
	v_mul_f32_e32 v136, v136, v139
	v_sub_f32_e32 v138, 1.0, v137
	v_add_f32_e32 v137, 1.0, v137
	v_mul_f32_e32 v137, v138, v137
	v_max_f32_e32 v137, 0, v137
	v_sqrt_f32_e32 v137, v137
	s_nop 0
	v_mul_f32_e32 v136, v137, v136
	v_cvt_pk_bf16_f32 v136, v136, s0
	ds_write_b16 v199, v136 offset:7600
	v_mul_f32_e32 v136, v124, v120
	v_rcp_f32_e32 v136, v136
	v_cvt_pk_bf16_f32 v137, v138, s0
	ds_write_b16 v198, v137 offset:7600
	v_mul_f32_e32 v120, v120, v136
	v_mul_f32_e32 v120, v205, v120
	v_mul_f32_e32 v120, 0x3fb8aa3b, v120
	v_exp_f32_e32 v120, v120
	v_mul_f32_e32 v124, v124, v136
	v_lshlrev_b32_e32 v137, 16, v234
	v_mul_f32_e32 v124, v124, v137
	v_sub_f32_e32 v136, 1.0, v120
	v_add_f32_e32 v120, 1.0, v120
	v_mul_f32_e32 v120, v136, v120
	v_max_f32_e32 v120, 0, v120
	v_sqrt_f32_e32 v120, v120
	s_nop 0
	v_mul_f32_e32 v120, v120, v124
	v_cvt_pk_bf16_f32 v120, v120, s0
	ds_write_b16 v199, v120 offset:12800
	v_add_f32_e32 v120, v125, v170
	v_min_f32_e64 v120, -v120, s93
	v_mul_f32_e32 v120, 0x3fb8aa3b, v120
	v_exp_f32_e32 v120, v120
	v_cvt_pk_bf16_f32 v124, v136, s0
	ds_write_b16 v198, v124 offset:12800
	v_add_f32_e32 v120, 1.0, v120
	v_mul_f32_e32 v124, v120, v121
	v_rcp_f32_e32 v124, v124
	v_lshlrev_b32_e32 v125, 16, v235
	v_mul_f32_e32 v121, v121, v124
	v_mul_f32_e32 v121, v205, v121
	v_mul_f32_e32 v121, 0x3fb8aa3b, v121
	v_exp_f32_e32 v121, v121
	v_mul_f32_e32 v120, v120, v124
	v_mul_f32_e32 v120, v120, v125
	v_sub_f32_e32 v124, 1.0, v121
	v_add_f32_e32 v121, 1.0, v121
	v_mul_f32_e32 v121, v124, v121
	v_max_f32_e32 v121, 0, v121
	v_sqrt_f32_e32 v121, v121
	s_nop 0
	v_mul_f32_e32 v120, v121, v120
	v_cvt_pk_bf16_f32 v121, v124, s0
	v_cvt_pk_bf16_f32 v120, v120, s0
	ds_write_b16 v198, v121 offset:13200
	ds_write_b16 v199, v120 offset:13200
	v_add_f32_e32 v120, v126, v170
	v_add_f32_e32 v121, v122, v171
	v_min_f32_e64 v120, -v120, s93
	v_min_f32_e64 v121, -v121, s93
	v_mul_f32_e32 v120, 0x3fb8aa3b, v120
	v_mul_f32_e32 v121, 0x3fb8aa3b, v121
	v_exp_f32_e32 v120, v120
	v_exp_f32_e32 v121, v121
	v_add_f32_e32 v120, 1.0, v120
	v_add_f32_e32 v121, 1.0, v121
	v_mul_f32_e32 v122, v120, v121
	v_rcp_f32_e32 v122, v122
	v_lshlrev_b32_e32 v124, 16, v236
	v_mul_f32_e32 v121, v121, v122
	v_mul_f32_e32 v121, v205, v121
	v_mul_f32_e32 v121, 0x3fb8aa3b, v121
	v_exp_f32_e32 v121, v121
	v_mul_f32_e32 v120, v120, v122
	v_mul_f32_e32 v120, v120, v124
	v_sub_f32_e32 v122, 1.0, v121
	v_add_f32_e32 v121, 1.0, v121
	v_mul_f32_e32 v121, v122, v121
	v_max_f32_e32 v121, 0, v121
	v_sqrt_f32_e32 v121, v121
	s_nop 0
	v_mul_f32_e32 v120, v121, v120
	v_cvt_pk_bf16_f32 v121, v122, s0
; #define LAS __attribute__((address_space(3)))
; DI unsigned pk2(float a, float b) { f32x2 v = {a, b}; bf2_t r = __builtin_convertvector(v, bf2_t); return __builtin_bit_cast(unsigned, r); }
; DI void phase_rglru(const Params& p, unsigned char* shm) {
;     ...
;                     const int ch = chb + 16 * u + fr;
;                     const float ba = gb[ch], bx = gb[192 + ch], sp = gb[384 + ch];
; #pragma unroll
;                     for (int mt = 0; mt < 4; ++mt)
; #pragma unroll
;                         for (int j = 0; j < 4; ++j) {
;                             const int t = 16 * mt + 4 * fq + j;
;                             const float ea = 1.f + __expf(fminf(-(acc[mt][0][j] + ba), 40.f)), ex = 1.f + __expf(fminf(-(acc[mt][1][j] + bx), 40.f));
;                             const float inv = __builtin_amdgcn_rcpf(ea * ex);
;                             const float r = inv * ex, ig = inv * ea;
;                             const float av = __expf(r * sp), om = 1.f - av;
;                             const float xcv = __uint_as_float((unsigned)*(const LAS bf16_t*)(lds + XC + t * TR + ch * 2) << 16);
;                             const float bt = __builtin_amdgcn_sqrtf(fmaxf(om * (1.f + av), 0.f)) * (ig * xcv);
;                             *(LAS bf16_t*)(lds + LAo + t * TR + ch * 2) = (bf16_t)(pk2(om, 0.f) & 0xffffu);
;                             *(LAS bf16_t*)(lds + BTo + t * TR + ch * 2) = (bf16_t)(pk2(bt, 0.f) & 0xffffu);
;                         }
	v_cvt_pk_bf16_f32 v120, v120, s0
	ds_write_b16 v198, v121 offset:13600
	ds_write_b16 v199, v120 offset:13600
	v_add_f32_e32 v120, v127, v170
	v_add_f32_e32 v121, v123, v171
	v_min_f32_e64 v120, -v120, s93
	v_min_f32_e64 v121, -v121, s93
	v_mul_f32_e32 v120, 0x3fb8aa3b, v120
	v_mul_f32_e32 v121, 0x3fb8aa3b, v121
	v_exp_f32_e32 v120, v120
	v_exp_f32_e32 v121, v121
	v_add_f32_e32 v120, 1.0, v120
	v_add_f32_e32 v121, 1.0, v121
	v_mul_f32_e32 v122, v120, v121
	v_rcp_f32_e32 v122, v122
	v_lshlrev_b32_e32 v123, 16, v237
	v_mul_f32_e32 v121, v121, v122
	v_mul_f32_e32 v121, v205, v121
	v_mul_f32_e32 v121, 0x3fb8aa3b, v121
	v_exp_f32_e32 v121, v121
	v_mul_f32_e32 v120, v120, v122
	v_mul_f32_e32 v120, v120, v123
	v_sub_f32_e32 v122, 1.0, v121
	v_add_f32_e32 v121, 1.0, v121
	v_mul_f32_e32 v121, v122, v121
	v_max_f32_e32 v121, 0, v121
	v_sqrt_f32_e32 v121, v121
	v_lshlrev_b32_e32 v123, 16, v238
	v_mul_f32_e32 v120, v121, v120
	v_cvt_pk_bf16_f32 v121, v122, s0
	v_cvt_pk_bf16_f32 v120, v120, s0
	ds_write_b16 v198, v121 offset:14000
	ds_write_b16 v199, v120 offset:14000
	v_add_f32_e32 v120, v132, v170
	v_add_f32_e32 v121, v128, v171
	v_min_f32_e64 v120, -v120, s93
	v_min_f32_e64 v121, -v121, s93
	v_mul_f32_e32 v120, 0x3fb8aa3b, v120
	v_mul_f32_e32 v121, 0x3fb8aa3b, v121
	v_exp_f32_e32 v120, v120
	v_exp_f32_e32 v121, v121
	v_add_f32_e32 v120, 1.0, v120
	v_add_f32_e32 v121, 1.0, v121
	v_mul_f32_e32 v122, v120, v121
	v_rcp_f32_e32 v122, v122
	s_nop 0
	v_mul_f32_e32 v121, v121, v122
	v_mul_f32_e32 v121, v205, v121
	v_mul_f32_e32 v121, 0x3fb8aa3b, v121
	v_exp_f32_e32 v121, v121
	v_mul_f32_e32 v120, v120, v122
	v_mul_f32_e32 v120, v120, v123
	v_sub_f32_e32 v122, 1.0, v121
	v_add_f32_e32 v121, 1.0, v121
	v_mul_f32_e32 v121, v122, v121
	v_max_f32_e32 v121, 0, v121
	v_sqrt_f32_e32 v121, v121
	v_lshlrev_b32_e32 v123, 16, v239
	v_mul_f32_e32 v120, v121, v120
	v_cvt_pk_bf16_f32 v121, v122, s0
	v_cvt_pk_bf16_f32 v120, v120, s0
	ds_write_b16 v198, v121 offset:19200
	ds_write_b16 v199, v120 offset:19200
	v_add_f32_e32 v120, v133, v170
	v_add_f32_e32 v121, v129, v171
	v_min_f32_e64 v120, -v120, s93
	v_min_f32_e64 v121, -v121, s93
	v_mul_f32_e32 v120, 0x3fb8aa3b, v120
	v_mul_f32_e32 v121, 0x3fb8aa3b, v121
	v_exp_f32_e32 v120, v120
	v_exp_f32_e32 v121, v121
	v_add_f32_e32 v120, 1.0, v120
	v_add_f32_e32 v121, 1.0, v121
	v_mul_f32_e32 v122, v120, v121
	v_rcp_f32_e32 v122, v122
	s_nop 0
	v_mul_f32_e32 v121, v121, v122
	v_mul_f32_e32 v121, v205, v121
	v_mul_f32_e32 v121, 0x3fb8aa3b, v121
	v_exp_f32_e32 v121, v121
	v_mul_f32_e32 v120, v120, v122
	v_mul_f32_e32 v120, v120, v123
	v_sub_f32_e32 v122, 1.0, v121
	v_add_f32_e32 v121, 1.0, v121
	v_mul_f32_e32 v121, v122, v121
	v_max_f32_e32 v121, 0, v121
	v_sqrt_f32_e32 v121, v121
	v_lshlrev_b32_e32 v123, 16, v240
	v_mul_f32_e32 v120, v121, v120
	v_cvt_pk_bf16_f32 v121, v122, s0
	v_cvt_pk_bf16_f32 v120, v120, s0
	ds_write_b16 v198, v121 offset:19600
	ds_write_b16 v199, v120 offset:19600
	v_add_f32_e32 v120, v134, v170
	v_add_f32_e32 v121, v130, v171
	v_min_f32_e64 v120, -v120, s93
	v_min_f32_e64 v121, -v121, s93
	v_mul_f32_e32 v120, 0x3fb8aa3b, v120
	v_mul_f32_e32 v121, 0x3fb8aa3b, v121
	v_exp_f32_e32 v120, v120
	v_exp_f32_e32 v121, v121
	v_add_f32_e32 v120, 1.0, v120
	v_add_f32_e32 v121, 1.0, v121
	v_mul_f32_e32 v122, v120, v121
	v_rcp_f32_e32 v122, v122
	s_nop 0
	v_mul_f32_e32 v121, v121, v122
	v_mul_f32_e32 v121, v205, v121
	v_mul_f32_e32 v121, 0x3fb8aa3b, v121
	v_exp_f32_e32 v121, v121
	v_mul_f32_e32 v120, v120, v122
	v_mul_f32_e32 v120, v120, v123
	v_sub_f32_e32 v122, 1.0, v121
	v_add_f32_e32 v121, 1.0, v121
	v_mul_f32_e32 v121, v122, v121
	v_max_f32_e32 v121, 0, v121
	v_sqrt_f32_e32 v121, v121
	v_lshlrev_b32_e32 v123, 16, v241
	v_mul_f32_e32 v120, v121, v120
	v_cvt_pk_bf16_f32 v121, v122, s0
	v_cvt_pk_bf16_f32 v120, v120, s0
	ds_write_b16 v198, v121 offset:20000
	ds_write_b16 v199, v120 offset:20000
	v_add_f32_e32 v120, v135, v170
	v_add_f32_e32 v121, v131, v171
	v_min_f32_e64 v120, -v120, s93
	v_min_f32_e64 v121, -v121, s93
	v_mul_f32_e32 v120, 0x3fb8aa3b, v120
	v_mul_f32_e32 v121, 0x3fb8aa3b, v121
	v_exp_f32_e32 v120, v120
	v_exp_f32_e32 v121, v121
	v_add_f32_e32 v120, 1.0, v120
	v_add_f32_e32 v121, 1.0, v121
	v_mul_f32_e32 v122, v120, v121
	v_rcp_f32_e32 v122, v122
	s_nop 0
	v_mul_f32_e32 v121, v121, v122
	v_mul_f32_e32 v121, v205, v121
	v_mul_f32_e32 v121, 0x3fb8aa3b, v121
	v_mul_f32_e32 v120, v120, v122
	v_exp_f32_e32 v122, v121
	v_mul_f32_e32 v120, v120, v123
	v_sub_f32_e32 v121, 1.0, v122
	v_add_f32_e32 v122, 1.0, v122
	v_mul_f32_e32 v122, v121, v122
	v_max_f32_e32 v122, 0, v122
	v_sqrt_f32_e32 v122, v122
	v_cvt_pk_bf16_f32 v121, v121, s0
	ds_write_b16 v198, v121 offset:20400
	v_mul_f32_e32 v120, v122, v120
	v_cvt_pk_bf16_f32 v120, v120, s0
	ds_write_b16 v199, v120 offset:20400
